# baseline (speedup 1.0000x reference)
; #define LDK(DST, KQ) _Pragma("unroll") for (int kc = 0; kc < 4; ++kc) DST[kc] = *(const bf16x8*)(Ks + ((KQ) * 16 + fr) * 136 + kc * 32 + fq * 8)
; DEVINL void attn_item(const Params& p, int item, char* smem, int wv) {
;     ...
;   const int qblk = 31 - (item >> 4), b = (item >> 2) & 3, kvh = item & 3;
;   const int q0 = qblk * 128, ntile = 2 * qblk + 2;
;   const int qlast = q0 + wid * 16 + 15;
;   u16* Ks = (u16*)smem;
;   u16* Vs = Ks + 64 * 136;
;   const size_t qtok = (size_t)b * SEQ + q0 + wid * 16 + fr;
;   bf16x8 qf[2][4];
; #pragma unroll
;   for (int hh = 0; hh < 2; ++hh)
; #pragma unroll
;     for (int kc = 0; kc < 4; ++kc)
;       qf[hh][kc] = *(const bf16x8*)(hb + qtok * HS + 2560 + (kvh * 2 + hh) * 128 + kc * 32 + fq * 8);
;   f32x4 o[2][8];
; #pragma unroll
;   for (int hh = 0; hh < 2; ++hh)
; #pragma unroll
;     for (int dt = 0; dt < 8; ++dt) o[hh][dt] = f32x4{0.f, 0.f, 0.f, 0.f};
;   float mrun[2] = {0.f, 0.f}, lsum[2] = {0.f, 0.f};
;   unsigned long long mw_next = bits[qtok * 64];
;   u32x4 rk[2], rv[2];
;   const u16* kg = hb + ((size_t)b * SEQ + (tid >> 4)) * HS + 3584 + kvh * 128 + (tid & 15) * 8;
;   const u16* vg = vT + ((size_t)(b * 4 + kvh) * 128 + (tid >> 3)) * SEQ + (tid & 7) * 8;
; #pragma unroll
;   for (int i = 0; i < 2; ++i) {
;     rk[i] = *(const u32x4*)(kg + (size_t)(32 * i) * HS);
;     rv[i] = *(const u32x4*)(vg + (size_t)(64 * i) * SEQ);
;   }
;   for (int kt = 0; kt < ntile; ++kt) {
; #pragma unroll
;     for (int i = 0; i < 2; ++i) {
;       *(u32x4*)(Ks + ((tid >> 4) + 32 * i) * 136 + (tid & 15) * 8) = rk[i];
;       *(u32x4*)(Vs + ((tid >> 3) + 64 * i) * 72 + (tid & 7) * 8) = rv[i];
;     }
;     __syncthreads();
;     if (kt + 1 < ntile) {
; #pragma unroll
;       for (int i = 0; i < 2; ++i) {
;         rk[i] = *(const u32x4*)(kg + (size_t)((kt + 1) * 64 + 32 * i) * HS);
;         rv[i] = *(const u32x4*)(vg + (size_t)(64 * i) * SEQ + (kt + 1) * 64);
;       }
;     }
;     const unsigned long long mw = mw_next;
;     if (kt + 1 < ntile) mw_next = bits[qtok * 64 + kt + 1];
;     if (kt * 64 <= qlast) {
;     f32x4 s[2][4];
;     bf16x8 kfa[4], kfb[4];
;     bf16x8 vfa[2], vfb[2];
;     ...
;     LDK(kfa, 0);
;     LDK(kfb, 1); MMS(kfa, 0);
;     LDK(kfa, 2); MMS(kfb, 1);
.LBB0_701:
	s_or_b64 exec, exec, s[0:1]
	s_waitcnt lgkmcnt(0)
	s_barrier
	ds_read_b32 v0, v170
	s_movk_i32 s0, 0x1ff
	s_waitcnt lgkmcnt(0)
	v_cmp_lt_i32_e32 vcc, s0, v0
	v_readfirstlane_b32 s5, v0
	s_mov_b64 s[0:1], -1
	s_cbranch_vccnz .LBB0_696
	v_mov_b32_e32 v120, v176
	s_ashr_i32 s29, s5, 4
	s_sub_i32 s30, 31, s29
	v_readfirstlane_b32 s0, v120
	s_lshl_b32 s1, s5, 10
	s_lshl_b32 s7, s30, 7
	s_ashr_i32 s31, s0, 2
	s_and_b32 s33, s1, 0x3000
	v_and_b32_e32 v60, 15, v120
	s_and_b32 s0, s31, -16
	s_add_i32 s8, s7, s33
	s_ashr_i32 s1, s0, 31
	v_or_b32_e32 v0, s8, v60
	s_waitcnt vmcnt(1)
	v_lshl_add_u64 v[156:157], v[0:1], 0, s[0:1]
	v_mov_b64_e32 v[2:3], s[62:63]
	v_mad_u64_u32 v[4:5], s[0:1], v156, s19, v[2:3]
	s_and_b32 s6, s5, 3
	v_mad_i32_i24 v5, v157, s19, v5
	v_and_b32_e32 v0, 48, v120
	v_lshl_add_u64 v[4:5], v[4:5], 0, v[0:1]
	s_lshl_b32 s8, s6, 9
	v_ashrrev_i32_e32 v14, 4, v120
	v_lshl_add_u64 v[8:9], v[4:5], 0, s[8:9]
	v_add_u32_e32 v4, s33, v14
	s_lshl_b32 s16, s6, 8
	s_mov_b32 s17, s9
	v_mad_i64_i32 v[2:3], s[0:1], v4, s19, v[2:3]
	v_lshlrev_b32_e32 v6, 4, v120
	v_lshl_add_u64 v[2:3], v[2:3], 0, s[16:17]
	v_and_b32_e32 v10, 0xf0, v6
	v_mov_b32_e32 v11, v1
	v_lshl_add_u64 v[116:117], v[2:3], 0, v[10:11]
	s_lshl_b32 s0, s5, 7
	v_ashrrev_i32_e32 v2, 3, v120
	s_and_b32 s8, s0, 0x780
	v_ashrrev_i32_e32 v3, 31, v2
	v_lshl_add_u64 v[4:5], v[2:3], 0, s[8:9]
	v_lshlrev_b64 v[4:5], 13, v[4:5]
	v_lshl_add_u64 v[4:5], s[82:83], 0, v[4:5]
	v_and_b32_e32 v12, 0x70, v6
	v_mov_b32_e32 v13, v1
	v_lshl_add_u64 v[158:159], v[4:5], 0, v[12:13]
	v_add_co_u32_e32 v4, vcc, s20, v116
	global_load_dwordx4 v[36:39], v[158:159], off
	s_nop 0
	v_addc_co_u32_e32 v5, vcc, 0, v117, vcc
	v_add_co_u32_e32 v6, vcc, s21, v116
	v_mul_lo_u32 v2, v2, s24
	s_nop 0
	v_addc_co_u32_e32 v7, vcc, 0, v117, vcc
	global_load_dwordx4 v[40:43], v[4:5], off offset:3072
	global_load_dwordx4 v[44:47], v[6:7], off offset:3072
	v_add_co_u32_e32 v52, vcc, s22, v158
	v_add_u32_e32 v11, 0, v12
	s_nop 0
	v_addc_co_u32_e32 v53, vcc, 0, v159, vcc
	global_load_dwordx4 v[48:51], v[52:53], off
	v_mul_lo_u32 v3, v14, s23
	v_add_u32_e32 v10, 0, v10
	v_and_b32_e32 v173, 64, v12
	v_bfe_u32 v11, v12, 4, 1
	v_lshl_or_b32 v173, v11, 5, v173
	v_bfe_u32 v11, v12, 5, 1
	v_lshl_or_b32 v173, v11, 3, v173
	v_add_u32_e32 v173, v173, v2
	v_add_co_u32_e64 v2, s[0:1], s20, v8
	v_lshl_add_u64 v[28:29], v[8:9], 0, s[10:11]
	v_add_u32_e32 v172, v10, v3
	v_lshlrev_b64 v[118:119], 9, v[156:157]
	v_add_co_u32_e32 v54, vcc, 0xa1000, v116
	v_addc_co_u32_e64 v3, s[0:1], 0, v9, s[0:1]
	global_load_dwordx4 v[4:7], v[28:29], off offset:64
	v_lshl_add_u64 v[56:57], s[80:81], 0, v[118:119]
	v_addc_co_u32_e32 v55, vcc, 0, v117, vcc
	global_load_dwordx4 v[8:11], v[28:29], off offset:128
	global_load_dwordx4 v[12:15], v[28:29], off offset:192
	global_load_dwordx4 v[16:19], v[28:29], off offset:256
	global_load_dwordx4 v[20:23], v[28:29], off offset:320
	global_load_dwordx4 v[24:27], v[28:29], off offset:384
	s_nop 0
	global_load_dwordx4 v[28:31], v[28:29], off offset:448
	s_nop 0
	global_load_dwordx4 v[32:35], v[2:3], off offset:1024
	s_nop 0
	global_load_dwordx2 v[2:3], v[56:57], off
	v_add_co_u32_e32 v58, vcc, 0xf1000, v116
	s_add_i32 s8, s31, s7
	s_nop 0
	v_addc_co_u32_e32 v59, vcc, 0, v117, vcc
	s_cmp_gt_i32 s8, -1
	s_mov_b64 s[0:1], -1
	s_waitcnt vmcnt(11)
	ds_write_b128 v172, v[40:43]
	ds_write_b64 v173, v[36:37] offset:17408
	ds_write_b64 v173, v[38:39] offset:17424
	s_waitcnt vmcnt(10)
	ds_write_b128 v172, v[44:47] offset:8704
	s_waitcnt vmcnt(9)
	ds_write_b64 v173, v[48:49] offset:26624
	ds_write_b64 v173, v[50:51] offset:26640
	s_waitcnt lgkmcnt(0)
	s_barrier
	global_load_dwordx4 v[44:47], v[58:59], off offset:3072
	global_load_dwordx4 v[36:39], v[54:55], off offset:3072
	global_load_dwordx4 v[48:51], v[52:53], off offset:128
	global_load_dwordx4 v[40:43], v[158:159], off offset:128
	global_load_dwordx2 v[162:163], v[56:57], off offset:8
	v_mad_u32_u24 v52, v60, s23, 0
	v_lshlrev_b32_e32 v53, 7, v60
	v_lshrrev_b32_e32 v54, 2, v120
	v_sub_u32_e32 v53, v52, v53
	v_and_b32_e32 v174, 12, v54
	v_add_u32_e32 v175, v52, v0
	v_lshl_add_u32 v177, v174, 2, v53
	s_cbranch_scc0 .LBB0_704
	ds_read_b128 v[52:55], v175
	ds_read_b128 v[56:59], v175 offset:64
	ds_read_b128 v[60:63], v175 offset:128
	ds_read_b128 v[64:67], v175 offset:192
	ds_read_b128 v[68:71], v175 offset:4352
	ds_read_b128 v[72:75], v175 offset:4416
	ds_read_b128 v[76:79], v175 offset:4480
	ds_read_b128 v[80:83], v175 offset:4544
	s_mov_b32 s6, s4
	s_mov_b32 s7, s4
	s_mov_b32 s5, s4
	v_mov_b64_e32 v[86:87], s[6:7]
	v_mov_b64_e32 v[84:85], s[4:5]
	s_waitcnt vmcnt(6) lgkmcnt(7)
	s_nop 0
	v_mfma_f32_16x16x32_bf16 v[88:91], v[52:55], v[32:35], v[84:87]
	v_mfma_f32_16x16x32_bf16 v[52:55], v[52:55], v[16:19], v[84:87]
	s_waitcnt lgkmcnt(6)
	v_mfma_f32_16x16x32_bf16 v[88:91], v[56:59], v[4:7], v[88:91]
	v_mfma_f32_16x16x32_bf16 v[52:55], v[56:59], v[20:23], v[52:55]
	s_waitcnt lgkmcnt(5)
	v_mfma_f32_16x16x32_bf16 v[56:59], v[60:63], v[8:11], v[88:91]
	v_mfma_f32_16x16x32_bf16 v[52:55], v[60:63], v[24:27], v[52:55]
	s_waitcnt lgkmcnt(4)
	v_mfma_f32_16x16x32_bf16 v[60:63], v[64:67], v[12:15], v[56:59]
	v_mfma_f32_16x16x32_bf16 v[64:67], v[64:67], v[28:31], v[52:55]
	s_nop 3
	s_nop 0
	ds_read_b128 v[52:55], v175 offset:8704
	ds_read_b128 v[56:59], v175 offset:8768
	ds_read_b128 v[88:91], v175 offset:8832
	ds_read_b128 v[92:95], v175 offset:8896
	s_waitcnt lgkmcnt(7)
	v_mfma_f32_16x16x32_bf16 v[96:99], v[68:71], v[32:35], v[84:87]
	v_mfma_f32_16x16x32_bf16 v[68:71], v[68:71], v[16:19], v[84:87]
	s_waitcnt lgkmcnt(6)
; DEVINL void attn_item(const Params& p, int item, char* smem, int wv) {
;     ...
;     LDK(kfa, 0);
;     LDK(kfb, 1); MMS(kfa, 0);
;     LDK(kfa, 2); MMS(kfb, 1);
;     LDK(kfb, 3); MMS(kfa, 2);
;     LDV(vfa, 0); MMS(kfb, 3);
;     bf16x8 pf[2][2];
;     {
;       const unsigned long long msh = mw >> (fq * 4);
;       const int mlo = (int)(unsigned)msh, mhi = (int)(unsigned)(msh >> 32);
;       int mk[4][4];
; #pragma unroll
;       for (int j = 0; j < 4; ++j) {
;         mk[0][j] = __builtin_amdgcn_sbfe(mlo, j, 1); mk[1][j] = __builtin_amdgcn_sbfe(mlo, 16 + j, 1);
;         mk[2][j] = __builtin_amdgcn_sbfe(mhi, j, 1); mk[3][j] = __builtin_amdgcn_sbfe(mhi, 16 + j, 1);
;       }
; #pragma unroll
;       for (int hh = 0; hh < 2; ++hh) {
;         float mx = s[hh][0][0];
; #pragma unroll
;         for (int kq = 0; kq < 4; ++kq)
; #pragma unroll
;           for (int j = 0; j < 4; ++j) mx = fmaxf(mx, s[hh][kq][j]);
;         {
;           auto r1 = __builtin_amdgcn_permlane16_swap(__float_as_uint(mx), __float_as_uint(mx), false, false);
;           mx = fmaxf(__uint_as_float(r1[0]), __uint_as_float(r1[1]));
;           auto r2 = __builtin_amdgcn_permlane32_swap(__float_as_uint(mx), __float_as_uint(mx), false, false);
;           mx = fmaxf(__uint_as_float(r2[0]), __uint_as_float(r2[1]));
;         }
;         if (kt == 0 || __ballot(mx > 8.f)) {
;           const float delta = (kt == 0) ? mx : fmaxf(mx, 0.f);
;           const float alpha = fexp2(-delta);
;           mrun[hh] += delta;
;           lsum[hh] *= alpha;
; #pragma unroll
;           for (int dt = 0; dt < 8; ++dt) o[hh][dt] *= alpha;
; #pragma unroll
;           for (int kq = 0; kq < 4; ++kq)
; #pragma unroll
;             for (int j = 0; j < 4; ++j) s[hh][kq][j] -= delta;
;         }
;         float ps = 0.f;
;         float pv[4][4];
; #pragma unroll
;         for (int kq = 0; kq < 4; ++kq)
; #pragma unroll
;           for (int j = 0; j < 4; ++j) {
;             pv[kq][j] = __uint_as_float(__float_as_uint(fexp2(s[hh][kq][j])) & (unsigned)mk[kq][j]);
;             ps += pv[kq][j];
;           }
; #pragma unroll
;         for (int c2 = 0; c2 < 2; ++c2) {
;           u32x4 pw;
;           pw[0] = pk2(pv[2 * c2][0], pv[2 * c2][1]); pw[1] = pk2(pv[2 * c2][2], pv[2 * c2][3]);
;           pw[2] = pk2(pv[2 * c2 + 1][0], pv[2 * c2 + 1][1]); pw[3] = pk2(pv[2 * c2 + 1][2], pv[2 * c2 + 1][3]);
	v_mfma_f32_16x16x32_bf16 v[96:99], v[72:75], v[4:7], v[96:99]
	v_mfma_f32_16x16x32_bf16 v[68:71], v[72:75], v[20:23], v[68:71]
	s_waitcnt lgkmcnt(5)
	v_mfma_f32_16x16x32_bf16 v[72:75], v[76:79], v[8:11], v[96:99]
	v_mfma_f32_16x16x32_bf16 v[68:71], v[76:79], v[24:27], v[68:71]
	s_waitcnt lgkmcnt(4)
	v_mfma_f32_16x16x32_bf16 v[72:75], v[80:83], v[12:15], v[72:75]
	v_mfma_f32_16x16x32_bf16 v[68:71], v[80:83], v[28:31], v[68:71]
	ds_read_b128 v[76:79], v175 offset:13056
	ds_read_b128 v[80:83], v175 offset:13120
	ds_read_b128 v[96:99], v175 offset:13184
	ds_read_b128 v[100:103], v175 offset:13248
	s_waitcnt lgkmcnt(7)
	v_mfma_f32_16x16x32_bf16 v[104:107], v[52:55], v[32:35], v[84:87]
	v_mfma_f32_16x16x32_bf16 v[52:55], v[52:55], v[16:19], v[84:87]
	s_waitcnt lgkmcnt(6)
	v_mfma_f32_16x16x32_bf16 v[104:107], v[56:59], v[4:7], v[104:107]
	v_mfma_f32_16x16x32_bf16 v[52:55], v[56:59], v[20:23], v[52:55]
	s_waitcnt lgkmcnt(5)
	v_mfma_f32_16x16x32_bf16 v[56:59], v[88:91], v[8:11], v[104:107]
	v_mfma_f32_16x16x32_bf16 v[52:55], v[88:91], v[24:27], v[52:55]
	s_waitcnt lgkmcnt(4)
	v_mfma_f32_16x16x32_bf16 v[88:91], v[92:95], v[12:15], v[56:59]
	v_mfma_f32_16x16x32_bf16 v[92:95], v[92:95], v[28:31], v[52:55]
	s_nop 2
	s_nop 0
	s_nop 0
	ds_read_b128 v[52:55], v177 offset:17408
	ds_read_b128 v[56:59], v177 offset:17472
	s_waitcnt lgkmcnt(5)
	v_mfma_f32_16x16x32_bf16 v[104:107], v[76:79], v[32:35], v[84:87]
	v_mfma_f32_16x16x32_bf16 v[76:79], v[76:79], v[16:19], v[84:87]
	s_waitcnt lgkmcnt(4)
	v_mfma_f32_16x16x32_bf16 v[84:87], v[80:83], v[4:7], v[104:107]
	v_mfma_f32_16x16x32_bf16 v[76:79], v[80:83], v[20:23], v[76:79]
	s_waitcnt lgkmcnt(3)
	v_mfma_f32_16x16x32_bf16 v[80:83], v[96:99], v[8:11], v[84:87]
	v_mfma_f32_16x16x32_bf16 v[76:79], v[96:99], v[24:27], v[76:79]
	s_waitcnt lgkmcnt(2)
	v_mfma_f32_16x16x32_bf16 v[80:83], v[100:103], v[12:15], v[80:83]
	v_mfma_f32_16x16x32_bf16 v[76:79], v[100:103], v[28:31], v[76:79]
	s_waitcnt vmcnt(5)
	v_lshrrev_b64 v[2:3], v174, v[2:3]
	v_bfe_i32 v0, v2, 0, 1
	v_bfe_i32 v86, v2, 16, 1
	v_bfe_i32 v87, v3, 0, 1
	v_bfe_i32 v96, v3, 16, 1
	v_bfe_i32 v97, v2, 1, 1
	v_bfe_i32 v98, v2, 17, 1
	v_bfe_i32 v99, v3, 1, 1
	v_bfe_i32 v104, v3, 17, 1
	v_bfe_i32 v100, v2, 2, 1
	v_bfe_i32 v101, v2, 18, 1
	v_bfe_i32 v105, v3, 2, 1
	v_bfe_i32 v106, v3, 18, 1
	v_bfe_i32 v102, v2, 3, 1
	v_bfe_i32 v103, v2, 19, 1
	v_bfe_i32 v107, v3, 3, 1
	v_bfe_i32 v108, v3, 19, 1
	v_max_f32_e32 v3, v60, v60
	v_max_f32_e32 v2, v3, v61
	v_max3_f32 v2, v2, v62, v63
	v_max3_f32 v2, v2, v72, v73
	v_max3_f32 v2, v2, v74, v75
	v_max3_f32 v2, v2, v88, v89
	v_max3_f32 v2, v2, v90, v91
	v_max3_f32 v2, v2, v80, v81
	v_max3_f32 v2, v2, v82, v83
	v_mov_b32_e32 v3, v2
	s_nop 1
	v_permlane16_swap_b32_e32 v2, v3
	v_max_f32_e32 v2, v2, v3
	v_mov_b32_e32 v3, v2
	s_nop 1
	v_permlane32_swap_b32_e32 v2, v3
	v_max_f32_e32 v3, v2, v3
	v_sub_f32_e32 v2, v80, v3
	v_sub_f32_e32 v61, v61, v3
	v_sub_f32_e32 v80, v81, v3
	v_sub_f32_e32 v81, v82, v3
	v_sub_f32_e32 v82, v83, v3
	v_sub_f32_e32 v83, v88, v3
	v_sub_f32_e32 v88, v90, v3
	v_exp_f32_e32 v90, v61
	v_exp_f32_e32 v115, v2
	v_max_f32_e32 v61, v64, v64
	v_max_f32_e32 v2, v61, v65
	v_max3_f32 v2, v2, v66, v67
	v_max3_f32 v2, v2, v68, v69
	v_max3_f32 v2, v2, v70, v71
	v_max3_f32 v2, v2, v92, v93
	v_max3_f32 v2, v2, v94, v95
	v_max3_f32 v2, v2, v76, v77
	v_max3_f32 v2, v2, v78, v79
	v_mov_b32_e32 v61, v2
	s_nop 1
	v_permlane16_swap_b32_e32 v2, v61
	v_max_f32_e32 v2, v2, v61
	v_mov_b32_e32 v61, v2
	s_nop 1
	v_permlane32_swap_b32_e32 v2, v61
	v_max_f32_e32 v2, v2, v61
	v_sub_f32_e32 v60, v60, v3
	v_sub_f32_e32 v64, v64, v2
	v_exp_f32_e32 v60, v60
	v_sub_f32_e32 v65, v65, v2
	v_exp_f32_e32 v64, v64
	v_sub_f32_e32 v62, v62, v3
	v_sub_f32_e32 v66, v66, v2
	v_exp_f32_e32 v65, v65
	v_sub_f32_e32 v85, v89, v3
	v_sub_f32_e32 v89, v91, v3
	v_sub_f32_e32 v63, v63, v3
	v_exp_f32_e32 v91, v62
	v_sub_f32_e32 v67, v67, v2
	v_exp_f32_e32 v66, v66
	v_sub_f32_e32 v72, v72, v3
	v_exp_f32_e32 v109, v63
	v_sub_f32_e32 v61, v68, v2
	v_sub_f32_e32 v62, v69, v2
	v_exp_f32_e32 v67, v67
	v_sub_f32_e32 v73, v73, v3
	v_exp_f32_e32 v72, v72
	v_exp_f32_e32 v113, v83
	v_exp_f32_e32 v125, v82
	v_sub_f32_e32 v82, v92, v2
	v_sub_f32_e32 v83, v93, v2
	v_sub_f32_e32 v63, v70, v2
	v_sub_f32_e32 v68, v71, v2
	v_exp_f32_e32 v70, v61
	v_exp_f32_e32 v71, v62
	v_and_b32_e32 v61, v0, v64
	v_and_b32_e32 v60, v0, v60
	v_and_b32_e32 v62, v97, v90
	v_sub_f32_e32 v74, v74, v3
	v_exp_f32_e32 v110, v73
	v_exp_f32_e32 v121, v80
	v_exp_f32_e32 v124, v81
	v_sub_f32_e32 v122, v76, v2
	v_sub_f32_e32 v126, v78, v2
	v_exp_f32_e32 v76, v63
	v_exp_f32_e32 v78, v68
	v_and_b32_e32 v63, v97, v65
	v_cvt_pk_bf16_f32 v68, v60, v62
	v_pk_add_f32 v[80:81], v[60:61], 0 op_sel_hi:[1,0]
	v_exp_f32_e32 v0, v82
	v_exp_f32_e32 v60, v83
	v_sub_f32_e32 v75, v75, v3
	v_exp_f32_e32 v111, v74
	v_and_b32_e32 v65, v100, v66
	v_and_b32_e32 v64, v100, v91
	v_pk_add_f32 v[80:81], v[80:81], v[62:63]
	v_exp_f32_e32 v112, v75
	v_and_b32_e32 v67, v102, v67
	v_and_b32_e32 v66, v102, v109
	v_pk_add_f32 v[80:81], v[80:81], v[64:65]
	v_sub_f32_e32 v93, v95, v2
	v_and_b32_e32 v73, v86, v70
	v_and_b32_e32 v72, v86, v72
	v_pk_add_f32 v[80:81], v[80:81], v[66:67]
	v_exp_f32_e32 v114, v85
	v_sub_f32_e32 v92, v94, v2
	v_and_b32_e32 v75, v98, v71
	v_and_b32_e32 v74, v98, v110
	v_pk_add_f32 v[80:81], v[80:81], v[72:73]
	v_and_b32_e32 v83, v87, v0
	v_and_b32_e32 v82, v87, v113
	v_and_b32_e32 v87, v99, v60
; DEVINL float fexp2(float x) { return __builtin_amdgcn_exp2f(x); }
; DEVINL uint32_t pk2(float a, float b) { hwf2 v = {a, b}; hwbf2 r = __builtin_convertvector(v, hwbf2); return *(uint32_t*)&r; }
; #define MMV(SRC, DT) do { __builtin_amdgcn_s_setprio(1); _Pragma("unroll") for (int c2 = 0; c2 < 2; ++c2) { o[0][DT] = mfma16(SRC[c2], pf[0][c2], o[0][DT]); o[1][DT] = mfma16(SRC[c2], pf[1][c2], o[1][DT]); } __builtin_amdgcn_s_setprio(0); } while (0)
; DEVINL void attn_item(const Params& p, int item, char* smem, int wv) {
;     ...
;         if (kt == 0 || __ballot(mx > 8.f)) {
;           const float delta = (kt == 0) ? mx : fmaxf(mx, 0.f);
;           const float alpha = fexp2(-delta);
;           mrun[hh] += delta;
;           lsum[hh] *= alpha;
; #pragma unroll
;           for (int dt = 0; dt < 8; ++dt) o[hh][dt] *= alpha;
; #pragma unroll
;           for (int kq = 0; kq < 4; ++kq)
; #pragma unroll
;             for (int j = 0; j < 4; ++j) s[hh][kq][j] -= delta;
;         }
;         float ps = 0.f;
;         float pv[4][4];
; #pragma unroll
;         for (int kq = 0; kq < 4; ++kq)
; #pragma unroll
;           for (int j = 0; j < 4; ++j) {
;             pv[kq][j] = __uint_as_float(__float_as_uint(fexp2(s[hh][kq][j])) & (unsigned)mk[kq][j]);
;             ps += pv[kq][j];
;           }
; #pragma unroll
;         for (int c2 = 0; c2 < 2; ++c2) {
;           u32x4 pw;
;           pw[0] = pk2(pv[2 * c2][0], pv[2 * c2][1]); pw[1] = pk2(pv[2 * c2][2], pv[2 * c2][3]);
;           pw[2] = pk2(pv[2 * c2 + 1][0], pv[2 * c2 + 1][1]); pw[3] = pk2(pv[2 * c2 + 1][2], pv[2 * c2 + 1][3]);
;           pf[hh][c2] = *(bf16x8*)&pw;
;         }
;         lsum[hh] += ps;
;       }
;     }
;     LDV(vfb, 1); MMV(vfa, 0);
;     LDV(vfa, 2); MMV(vfb, 1);
;     LDV(vfb, 3); MMV(vfa, 2);
;     LDV(vfa, 4); MMV(vfb, 3);
;     LDV(vfb, 5); MMV(vfa, 4);
;     LDV(vfa, 6); MMV(vfb, 5);
;     LDV(vfb, 7); MMV(vfa, 6);
;     MMV(vfb, 7);
	v_exp_f32_e32 v60, v93
	v_exp_f32_e32 v88, v88
	v_sub_f32_e32 v123, v77, v2
	v_and_b32_e32 v77, v101, v76
	v_and_b32_e32 v76, v101, v111
	v_pk_add_f32 v[80:81], v[80:81], v[74:75]
	v_exp_f32_e32 v0, v92
	v_exp_f32_e32 v89, v89
	v_sub_f32_e32 v127, v79, v2
	v_and_b32_e32 v79, v103, v78
	v_and_b32_e32 v78, v103, v112
	v_pk_add_f32 v[80:81], v[80:81], v[76:77]
	v_exp_f32_e32 v62, v122
	v_pk_add_f32 v[80:81], v[80:81], v[78:79]
	v_cvt_pk_bf16_f32 v69, v64, v66
	v_and_b32_e32 v86, v99, v114
	v_exp_f32_e32 v64, v123
	v_cvt_pk_bf16_f32 v100, v61, v63
	v_cvt_pk_bf16_f32 v102, v73, v75
	v_and_b32_e32 v75, v107, v60
	v_pk_add_f32 v[60:61], v[80:81], v[82:83]
	v_cvt_pk_bf16_f32 v70, v72, v74
	v_exp_f32_e32 v66, v126
	v_and_b32_e32 v73, v105, v0
	v_and_b32_e32 v72, v105, v88
	v_pk_add_f32 v[60:61], v[60:61], v[86:87]
	v_exp_f32_e32 v90, v127
	v_and_b32_e32 v74, v107, v89
	v_pk_add_f32 v[60:61], v[60:61], v[72:73]
	v_cvt_pk_bf16_f32 v71, v76, v78
	v_cvt_pk_bf16_f32 v103, v77, v79
	v_and_b32_e32 v77, v96, v62
	v_and_b32_e32 v76, v96, v115
	v_pk_add_f32 v[60:61], v[60:61], v[74:75]
	v_and_b32_e32 v79, v104, v64
	v_and_b32_e32 v78, v104, v121
	v_pk_add_f32 v[60:61], v[60:61], v[76:77]
	v_and_b32_e32 v89, v106, v66
	v_and_b32_e32 v88, v106, v124
	v_pk_add_f32 v[60:61], v[60:61], v[78:79]
	v_and_b32_e32 v91, v108, v90
	v_and_b32_e32 v90, v108, v125
	v_pk_add_f32 v[60:61], v[60:61], v[88:89]
	v_exp_f32_e64 v84, -v3
	v_exp_f32_e64 v85, -v2
	v_cvt_pk_bf16_f32 v101, v65, v67
	v_pk_add_f32 v[80:81], v[60:61], v[90:91]
	ds_read_b128 v[60:63], v177 offset:19712
	ds_read_b128 v[64:67], v177 offset:19776
	v_pk_add_f32 v[2:3], v[2:3], 0 op_sel_hi:[1,0]
	v_pk_mul_f32 v[122:123], v[84:85], 0 op_sel_hi:[1,0]
	v_pk_fma_f32 v[160:161], v[84:85], 0, v[80:81] op_sel_hi:[1,0,1]
	v_mov_b32_e32 v126, v122
	v_mov_b32_e32 v127, v122
	v_mov_b32_e32 v128, v122
	v_mov_b32_e32 v129, v122
	v_cvt_pk_bf16_f32 v130, v82, v86
	v_cvt_pk_bf16_f32 v131, v72, v74
	v_cvt_pk_bf16_f32 v132, v76, v78
	v_cvt_pk_bf16_f32 v133, v88, v90
	v_mov_b32_e32 v122, v123
	v_mov_b32_e32 v124, v123
	v_mov_b32_e32 v125, v123
	v_cvt_pk_bf16_f32 v134, v83, v87
	v_cvt_pk_bf16_f32 v135, v73, v75
	v_cvt_pk_bf16_f32 v136, v77, v79
	v_cvt_pk_bf16_f32 v137, v89, v91
	s_waitcnt lgkmcnt(3)
	v_mfma_f32_16x16x32_bf16 v[72:75], v[52:55], v[68:71], v[126:129]
	v_mfma_f32_16x16x32_bf16 v[52:55], v[52:55], v[100:103], v[122:125]
	s_waitcnt lgkmcnt(2)
	v_mfma_f32_16x16x32_bf16 v[88:91], v[56:59], v[130:133], v[72:75]
	v_mfma_f32_16x16x32_bf16 v[52:55], v[56:59], v[134:137], v[52:55]
	s_nop 1
	s_nop 0
	s_nop 0
	ds_read_b128 v[72:75], v177 offset:22016
	ds_read_b128 v[76:79], v177 offset:22080
	s_waitcnt lgkmcnt(3)
	v_mfma_f32_16x16x32_bf16 v[56:59], v[60:63], v[68:71], v[126:129]
	v_mfma_f32_16x16x32_bf16 v[60:63], v[60:63], v[100:103], v[122:125]
	s_waitcnt lgkmcnt(2)
	v_mfma_f32_16x16x32_bf16 v[84:87], v[64:67], v[130:133], v[56:59]
	v_mfma_f32_16x16x32_bf16 v[56:59], v[64:67], v[134:137], v[60:63]
	ds_read_b128 v[64:67], v177 offset:24320
	ds_read_b128 v[80:83], v177 offset:24384
	s_waitcnt lgkmcnt(3)
	v_mfma_f32_16x16x32_bf16 v[60:63], v[72:75], v[68:71], v[126:129]
	v_mfma_f32_16x16x32_bf16 v[72:75], v[72:75], v[100:103], v[122:125]
	s_waitcnt lgkmcnt(2)
	v_mfma_f32_16x16x32_bf16 v[92:95], v[76:79], v[130:133], v[60:63]
	v_mfma_f32_16x16x32_bf16 v[60:63], v[76:79], v[134:137], v[72:75]
	s_nop 2
	s_nop 0
	s_nop 0
	ds_read_b128 v[72:75], v177 offset:26624
	ds_read_b128 v[76:79], v177 offset:26688
	s_waitcnt lgkmcnt(3)
	v_mfma_f32_16x16x32_bf16 v[96:99], v[64:67], v[68:71], v[126:129]
	v_mfma_f32_16x16x32_bf16 v[64:67], v[64:67], v[100:103], v[122:125]
	s_waitcnt lgkmcnt(2)
	v_mfma_f32_16x16x32_bf16 v[96:99], v[80:83], v[130:133], v[96:99]
	v_mfma_f32_16x16x32_bf16 v[64:67], v[80:83], v[134:137], v[64:67]
	ds_read_b128 v[80:83], v177 offset:28928
	ds_read_b128 v[112:115], v177 offset:28992
	s_waitcnt lgkmcnt(3)
	v_mfma_f32_16x16x32_bf16 v[104:107], v[72:75], v[68:71], v[126:129]
	v_mfma_f32_16x16x32_bf16 v[72:75], v[72:75], v[100:103], v[122:125]
	s_waitcnt lgkmcnt(2)
	v_mfma_f32_16x16x32_bf16 v[104:107], v[76:79], v[130:133], v[104:107]
	v_mfma_f32_16x16x32_bf16 v[72:75], v[76:79], v[134:137], v[72:75]
	ds_read_b128 v[138:141], v177 offset:31232
	ds_read_b128 v[142:145], v177 offset:31296
	s_waitcnt lgkmcnt(3)
	v_mfma_f32_16x16x32_bf16 v[76:79], v[80:83], v[68:71], v[126:129]
	v_mfma_f32_16x16x32_bf16 v[80:83], v[80:83], v[100:103], v[122:125]
	s_waitcnt lgkmcnt(2)
	v_mfma_f32_16x16x32_bf16 v[108:111], v[112:115], v[130:133], v[76:79]
	v_mfma_f32_16x16x32_bf16 v[76:79], v[112:115], v[134:137], v[80:83]
	ds_read_b128 v[146:149], v177 offset:33536
	ds_read_b128 v[150:153], v177 offset:33600
	s_waitcnt lgkmcnt(3)
	v_mfma_f32_16x16x32_bf16 v[80:83], v[138:141], v[68:71], v[126:129]
	v_mfma_f32_16x16x32_bf16 v[138:141], v[138:141], v[100:103], v[122:125]
	s_waitcnt lgkmcnt(2)
	v_mfma_f32_16x16x32_bf16 v[112:115], v[142:145], v[130:133], v[80:83]
	v_mfma_f32_16x16x32_bf16 v[80:83], v[142:145], v[134:137], v[138:141]
	s_waitcnt lgkmcnt(1)
	v_mfma_f32_16x16x32_bf16 v[68:71], v[146:149], v[68:71], v[126:129]
	v_mfma_f32_16x16x32_bf16 v[122:125], v[146:149], v[100:103], v[122:125]
	s_waitcnt lgkmcnt(0)
	v_mfma_f32_16x16x32_bf16 v[100:103], v[150:153], v[130:133], v[68:71]
	v_mfma_f32_16x16x32_bf16 v[68:71], v[150:153], v[134:137], v[122:125]
	s_cbranch_execz .LBB0_705
	s_branch .LBB0_706

; DEVINL float fexp2(float x) { return __builtin_amdgcn_exp2f(x); }
; #define LDK(DST, KQ) _Pragma("unroll") for (int kc = 0; kc < 4; ++kc) DST[kc] = *(const bf16x8*)(Ks + ((KQ) * 16 + fr) * 136 + kc * 32 + fq * 8)
; DEVINL void attn_item(const Params& p, int item, char* smem, int wv) {
;     ...
;     if (kt * 64 <= qlast) {
;     f32x4 s[2][4];
;     bf16x8 kfa[4], kfb[4];
;     bf16x8 vfa[2], vfb[2];
;     ...
;     LDK(kfa, 0);
;     LDK(kfb, 1); MMS(kfa, 0);
;     LDK(kfa, 2); MMS(kfb, 1);
;     LDK(kfb, 3); MMS(kfa, 2);
;     LDV(vfa, 0); MMS(kfb, 3);
;     bf16x8 pf[2][2];
;     {
;       const unsigned long long msh = mw >> (fq * 4);
;       const int mlo = (int)(unsigned)msh, mhi = (int)(unsigned)(msh >> 32);
;       int mk[4][4];
; #pragma unroll
;       for (int j = 0; j < 4; ++j) {
;         mk[0][j] = __builtin_amdgcn_sbfe(mlo, j, 1); mk[1][j] = __builtin_amdgcn_sbfe(mlo, 16 + j, 1);
;         mk[2][j] = __builtin_amdgcn_sbfe(mhi, j, 1); mk[3][j] = __builtin_amdgcn_sbfe(mhi, 16 + j, 1);
;       }
; #pragma unroll
;       for (int hh = 0; hh < 2; ++hh) {
;         float mx = s[hh][0][0];
; #pragma unroll
;         for (int kq = 0; kq < 4; ++kq)
; #pragma unroll
;           for (int j = 0; j < 4; ++j) mx = fmaxf(mx, s[hh][kq][j]);
;         {
;           auto r1 = __builtin_amdgcn_permlane16_swap(__float_as_uint(mx), __float_as_uint(mx), false, false);
;           mx = fmaxf(__uint_as_float(r1[0]), __uint_as_float(r1[1]));
;           auto r2 = __builtin_amdgcn_permlane32_swap(__float_as_uint(mx), __float_as_uint(mx), false, false);
;           mx = fmaxf(__uint_as_float(r2[0]), __uint_as_float(r2[1]));
;         }
;         if (kt == 0 || __ballot(mx > 8.f)) {
;           const float delta = (kt == 0) ? mx : fmaxf(mx, 0.f);
;           const float alpha = fexp2(-delta);
;           mrun[hh] += delta;
;           lsum[hh] *= alpha;
; #pragma unroll
;           for (int dt = 0; dt < 8; ++dt) o[hh][dt] *= alpha;
; #pragma unroll
;           for (int kq = 0; kq < 4; ++kq)
; #pragma unroll
;             for (int j = 0; j < 4; ++j) s[hh][kq][j] -= delta;
.LBB0_709:
	s_add_i32 s8, s6, 0xffffffa0
	s_cmp_gt_i32 s8, s1
	s_cbranch_scc1 .LBB0_715
	ds_read_b128 v[116:119], v175
	ds_read_b128 v[120:123], v175 offset:64
	ds_read_b128 v[124:127], v175 offset:128
	ds_read_b128 v[128:131], v175 offset:192
	ds_read_b128 v[132:135], v175 offset:4352
	ds_read_b128 v[140:143], v175 offset:4416
	ds_read_b128 v[144:147], v175 offset:4480
	ds_read_b128 v[178:181], v175 offset:4544
	v_xor_b32_e32 v182, 0x80000000, v3
	v_xor_b32_e32 v186, 0x80000000, v2
	v_mov_b32_e32 v183, v182
	v_mov_b32_e32 v184, v182
	v_mov_b32_e32 v185, v182
	v_mov_b32_e32 v187, v186
	v_mov_b32_e32 v188, v186
	v_mov_b32_e32 v189, v186
	s_waitcnt lgkmcnt(7)
	v_mfma_f32_16x16x32_bf16 v[136:139], v[116:119], v[32:35], v[182:185]
	v_mfma_f32_16x16x32_bf16 v[116:119], v[116:119], v[16:19], v[186:189]
	s_waitcnt lgkmcnt(6)
	v_mfma_f32_16x16x32_bf16 v[136:139], v[120:123], v[4:7], v[136:139]
	v_mfma_f32_16x16x32_bf16 v[116:119], v[120:123], v[20:23], v[116:119]
	s_waitcnt lgkmcnt(5)
	v_mfma_f32_16x16x32_bf16 v[120:123], v[124:127], v[8:11], v[136:139]
	v_mfma_f32_16x16x32_bf16 v[116:119], v[124:127], v[24:27], v[116:119]
	s_waitcnt lgkmcnt(4)
	v_mfma_f32_16x16x32_bf16 v[152:155], v[128:131], v[12:15], v[120:123]
	v_mfma_f32_16x16x32_bf16 v[136:139], v[128:131], v[28:31], v[116:119]
	s_nop 3
	s_nop 0
	ds_read_b128 v[116:119], v175 offset:8704
	ds_read_b128 v[120:123], v175 offset:8768
	ds_read_b128 v[124:127], v175 offset:8832
	ds_read_b128 v[128:131], v175 offset:8896
	s_waitcnt lgkmcnt(7)
	v_mfma_f32_16x16x32_bf16 v[148:151], v[132:135], v[32:35], v[182:185]
	v_mfma_f32_16x16x32_bf16 v[132:135], v[132:135], v[16:19], v[186:189]
	s_waitcnt lgkmcnt(6)
	v_mfma_f32_16x16x32_bf16 v[148:151], v[140:143], v[4:7], v[148:151]
	v_mfma_f32_16x16x32_bf16 v[132:135], v[140:143], v[20:23], v[132:135]
	s_waitcnt lgkmcnt(5)
	v_mfma_f32_16x16x32_bf16 v[140:143], v[144:147], v[8:11], v[148:151]
	v_mfma_f32_16x16x32_bf16 v[132:135], v[144:147], v[24:27], v[132:135]
	s_waitcnt lgkmcnt(4)
	v_mfma_f32_16x16x32_bf16 v[148:151], v[178:181], v[12:15], v[140:143]
	v_mfma_f32_16x16x32_bf16 v[132:135], v[178:181], v[28:31], v[132:135]
	ds_read_b128 v[144:147], v175 offset:13056
	ds_read_b128 v[178:181], v175 offset:13120
	ds_read_b128 v[190:193], v175 offset:13184
	ds_read_b128 v[194:197], v175 offset:13248
	s_waitcnt lgkmcnt(7)
	v_mfma_f32_16x16x32_bf16 v[140:143], v[116:119], v[32:35], v[182:185]
	v_mfma_f32_16x16x32_bf16 v[116:119], v[116:119], v[16:19], v[186:189]
	s_waitcnt lgkmcnt(6)
	v_mfma_f32_16x16x32_bf16 v[140:143], v[120:123], v[4:7], v[140:143]
	v_mfma_f32_16x16x32_bf16 v[116:119], v[120:123], v[20:23], v[116:119]
	s_waitcnt lgkmcnt(5)
	v_mfma_f32_16x16x32_bf16 v[120:123], v[124:127], v[8:11], v[140:143]
	v_mfma_f32_16x16x32_bf16 v[116:119], v[124:127], v[24:27], v[116:119]
	s_waitcnt lgkmcnt(4)
	v_mfma_f32_16x16x32_bf16 v[140:143], v[128:131], v[12:15], v[120:123]
	v_mfma_f32_16x16x32_bf16 v[124:127], v[128:131], v[28:31], v[116:119]
	s_nop 2
	s_nop 0
	s_nop 0
	ds_read_b128 v[116:119], v177 offset:17408
	ds_read_b128 v[120:123], v177 offset:17472
	s_waitcnt lgkmcnt(5)
	v_mfma_f32_16x16x32_bf16 v[128:131], v[144:147], v[32:35], v[182:185]
	v_mfma_f32_16x16x32_bf16 v[144:147], v[144:147], v[16:19], v[186:189]
	s_waitcnt lgkmcnt(4)
	v_mfma_f32_16x16x32_bf16 v[128:131], v[178:181], v[4:7], v[128:131]
	v_mfma_f32_16x16x32_bf16 v[144:147], v[178:181], v[20:23], v[144:147]
	s_waitcnt lgkmcnt(3)
	v_mfma_f32_16x16x32_bf16 v[128:131], v[190:193], v[8:11], v[128:131]
	v_mfma_f32_16x16x32_bf16 v[178:181], v[190:193], v[24:27], v[144:147]
	s_waitcnt lgkmcnt(2)
	v_mfma_f32_16x16x32_bf16 v[144:147], v[194:197], v[12:15], v[128:131]
	v_mfma_f32_16x16x32_bf16 v[128:131], v[194:197], v[28:31], v[178:181]
	s_nop 3
	s_nop 0
	v_max_f32_e32 v179, v152, v152
	v_max_f32_e32 v178, v179, v153
	v_max3_f32 v178, v178, v154, v155
	v_max3_f32 v178, v178, v148, v149
	v_max3_f32 v178, v178, v150, v151
	v_max3_f32 v178, v178, v140, v141
	v_max3_f32 v178, v178, v142, v143
	v_max3_f32 v178, v178, v144, v145
	v_max3_f32 v178, v178, v146, v147
	v_mov_b32_e32 v179, v178
	s_nop 1
	v_permlane16_swap_b32_e32 v178, v179
	v_max_f32_e32 v178, v178, v179
	v_mov_b32_e32 v179, v178
	s_nop 1
	v_permlane32_swap_b32_e32 v178, v179
	v_max_f32_e32 v178, v178, v179
	v_cmp_lt_f32_e32 vcc, s25, v178
	s_cbranch_vccz .LBB0_712
	v_max_f32_e32 v178, 0, v178
	v_exp_f32_e64 v180, -v178
	v_add_f32_e32 v3, v3, v178
	v_pk_add_f32 v[152:153], v[152:153], v[178:179] op_sel_hi:[1,0] neg_lo:[0,1] neg_hi:[0,1]
	v_pk_add_f32 v[154:155], v[154:155], v[178:179] op_sel_hi:[1,0] neg_lo:[0,1] neg_hi:[0,1]
	v_mul_f32_e32 v160, v160, v180
	v_pk_mul_f32 v[90:91], v[90:91], v[180:181] op_sel_hi:[1,0]
	v_pk_mul_f32 v[88:89], v[88:89], v[180:181] op_sel_hi:[1,0]
	v_pk_mul_f32 v[86:87], v[86:87], v[180:181] op_sel_hi:[1,0]
	v_pk_mul_f32 v[84:85], v[84:85], v[180:181] op_sel_hi:[1,0]
	v_pk_mul_f32 v[94:95], v[94:95], v[180:181] op_sel_hi:[1,0]
	v_pk_mul_f32 v[92:93], v[92:93], v[180:181] op_sel_hi:[1,0]
	v_pk_mul_f32 v[98:99], v[98:99], v[180:181] op_sel_hi:[1,0]
	v_pk_mul_f32 v[96:97], v[96:97], v[180:181] op_sel_hi:[1,0]
	v_pk_mul_f32 v[106:107], v[106:107], v[180:181] op_sel_hi:[1,0]
	v_pk_mul_f32 v[104:105], v[104:105], v[180:181] op_sel_hi:[1,0]
	v_pk_mul_f32 v[110:111], v[110:111], v[180:181] op_sel_hi:[1,0]
	v_pk_mul_f32 v[108:109], v[108:109], v[180:181] op_sel_hi:[1,0]
	v_pk_mul_f32 v[114:115], v[114:115], v[180:181] op_sel_hi:[1,0]
	v_pk_mul_f32 v[112:113], v[112:113], v[180:181] op_sel_hi:[1,0]
	v_pk_mul_f32 v[102:103], v[102:103], v[180:181] op_sel_hi:[1,0]
	v_pk_mul_f32 v[100:101], v[100:101], v[180:181] op_sel_hi:[1,0]
	v_pk_add_f32 v[148:149], v[148:149], v[178:179] op_sel_hi:[1,0] neg_lo:[0,1] neg_hi:[0,1]
	v_pk_add_f32 v[150:151], v[150:151], v[178:179] op_sel_hi:[1,0] neg_lo:[0,1] neg_hi:[0,1]
	v_pk_add_f32 v[140:141], v[140:141], v[178:179] op_sel_hi:[1,0] neg_lo:[0,1] neg_hi:[0,1]
	v_pk_add_f32 v[142:143], v[142:143], v[178:179] op_sel_hi:[1,0] neg_lo:[0,1] neg_hi:[0,1]
	v_pk_add_f32 v[144:145], v[144:145], v[178:179] op_sel_hi:[1,0] neg_lo:[0,1] neg_hi:[0,1]
	v_pk_add_f32 v[146:147], v[146:147], v[178:179] op_sel_hi:[1,0] neg_lo:[0,1] neg_hi:[0,1]

; #define LDK(DST, KQ) _Pragma("unroll") for (int kc = 0; kc < 4; ++kc) DST[kc] = *(const bf16x8*)(Ks + ((KQ) * 16 + fr) * 136 + kc * 32 + fq * 8)
; DEVINL void attn_item(const Params& p, int item, char* smem, int wv) {
;     ...
;   const int qblk = 31 - (item >> 4), b = (item >> 2) & 3, kvh = item & 3;
;   const int q0 = qblk * 128, ntile = 2 * qblk + 2;
;   const int qlast = q0 + wid * 16 + 15;
;   u16* Ks = (u16*)smem;
;   u16* Vs = Ks + 64 * 136;
;   const size_t qtok = (size_t)b * SEQ + q0 + wid * 16 + fr;
;   bf16x8 qf[2][4];
; #pragma unroll
;   for (int hh = 0; hh < 2; ++hh)
; #pragma unroll
;     for (int kc = 0; kc < 4; ++kc)
;       qf[hh][kc] = *(const bf16x8*)(hb + qtok * HS + 2560 + (kvh * 2 + hh) * 128 + kc * 32 + fq * 8);
;   f32x4 o[2][8];
; #pragma unroll
;   for (int hh = 0; hh < 2; ++hh)
; #pragma unroll
;     for (int dt = 0; dt < 8; ++dt) o[hh][dt] = f32x4{0.f, 0.f, 0.f, 0.f};
;   float mrun[2] = {0.f, 0.f}, lsum[2] = {0.f, 0.f};
;   unsigned long long mw_next = bits[qtok * 64];
;   u32x4 rk[2], rv[2];
;   const u16* kg = hb + ((size_t)b * SEQ + (tid >> 4)) * HS + 3584 + kvh * 128 + (tid & 15) * 8;
;   const u16* vg = vT + ((size_t)(b * 4 + kvh) * 128 + (tid >> 3)) * SEQ + (tid & 7) * 8;
; #pragma unroll
;   for (int i = 0; i < 2; ++i) {
;     rk[i] = *(const u32x4*)(kg + (size_t)(32 * i) * HS);
;     rv[i] = *(const u32x4*)(vg + (size_t)(64 * i) * SEQ);
;   }
;   for (int kt = 0; kt < ntile; ++kt) {
; #pragma unroll
;     for (int i = 0; i < 2; ++i) {
;       *(u32x4*)(Ks + ((tid >> 4) + 32 * i) * 136 + (tid & 15) * 8) = rk[i];
;       *(u32x4*)(Vs + ((tid >> 3) + 64 * i) * 72 + (tid & 7) * 8) = rv[i];
;     }
;     __syncthreads();
;     if (kt + 1 < ntile) {
; #pragma unroll
;       for (int i = 0; i < 2; ++i) {
;         rk[i] = *(const u32x4*)(kg + (size_t)((kt + 1) * 64 + 32 * i) * HS);
;         rv[i] = *(const u32x4*)(vg + (size_t)(64 * i) * SEQ + (kt + 1) * 64);
;       }
;     }
;     const unsigned long long mw = mw_next;
;     if (kt + 1 < ntile) mw_next = bits[qtok * 64 + kt + 1];
;     if (kt * 64 <= qlast) {
;     f32x4 s[2][4];
;     bf16x8 kfa[4], kfb[4];
;     bf16x8 vfa[2], vfb[2];
;     ...
;     LDK(kfa, 0);
;     LDK(kfb, 1); MMS(kfa, 0);
;     LDK(kfa, 2); MMS(kfb, 1);
.LBB0_1723:
	s_or_b64 exec, exec, s[2:3]
	s_waitcnt lgkmcnt(0)
	s_barrier
	ds_read_b32 v0, v170
	s_mov_b64 s[2:3], -1
	s_waitcnt lgkmcnt(0)
	v_cmp_lt_i32_e32 vcc, s21, v0
	v_readfirstlane_b32 s1, v0
	s_cbranch_vccnz .LBB0_1718
	s_waitcnt vmcnt(1)
	v_mov_b32_e32 v120, v176
	s_ashr_i32 s33, s1, 4
	s_sub_i32 s0, 31, s33
	v_readfirstlane_b32 s2, v120
	s_lshl_b32 s3, s1, 10
	s_lshl_b32 s6, s0, 7
	s_ashr_i32 s7, s2, 2
	s_and_b32 s34, s3, 0x3000
	v_and_b32_e32 v60, 15, v120
	s_and_b32 s2, s7, -16
	s_add_i32 s10, s6, s34
	s_ashr_i32 s3, s2, 31
	v_or_b32_e32 v0, s10, v60
	v_lshl_add_u64 v[156:157], v[0:1], 0, s[2:3]
	v_mov_b64_e32 v[2:3], s[62:63]
	v_mad_u64_u32 v[4:5], s[2:3], v156, s22, v[2:3]
	s_and_b32 s5, s1, 3
	v_mad_i32_i24 v5, v157, s22, v5
	v_and_b32_e32 v0, 48, v120
	v_lshl_add_u64 v[4:5], v[4:5], 0, v[0:1]
	s_lshl_b32 s10, s5, 9
	v_ashrrev_i32_e32 v14, 4, v120
	v_lshl_add_u64 v[8:9], v[4:5], 0, s[10:11]
	v_add_u32_e32 v4, s34, v14
	s_lshl_b32 s18, s5, 8
	s_mov_b32 s19, s11
	v_mad_i64_i32 v[2:3], s[2:3], v4, s22, v[2:3]
	v_lshlrev_b32_e32 v6, 4, v120
	v_lshl_add_u64 v[2:3], v[2:3], 0, s[18:19]
	v_and_b32_e32 v10, 0xf0, v6
	v_mov_b32_e32 v11, v1
	v_lshl_add_u64 v[116:117], v[2:3], 0, v[10:11]
	s_lshl_b32 s1, s1, 7
	v_ashrrev_i32_e32 v2, 3, v120
	s_and_b32 s10, s1, 0x780
	v_ashrrev_i32_e32 v3, 31, v2
	v_lshl_add_u64 v[4:5], v[2:3], 0, s[10:11]
	v_lshlrev_b64 v[4:5], 13, v[4:5]
	v_lshl_add_u64 v[4:5], s[40:41], 0, v[4:5]
	v_and_b32_e32 v12, 0x70, v6
	v_mov_b32_e32 v13, v1
	v_lshl_add_u64 v[158:159], v[4:5], 0, v[12:13]
	v_add_co_u32_e32 v4, vcc, s23, v116
	global_load_dwordx4 v[36:39], v[158:159], off
	s_nop 0
	v_addc_co_u32_e32 v5, vcc, 0, v117, vcc
	v_add_co_u32_e32 v6, vcc, s24, v116
	v_mul_lo_u32 v2, v2, s27
	s_nop 0
	v_addc_co_u32_e32 v7, vcc, 0, v117, vcc
	global_load_dwordx4 v[40:43], v[4:5], off offset:3072
	global_load_dwordx4 v[44:47], v[6:7], off offset:3072
	v_add_co_u32_e32 v52, vcc, s25, v158
	v_add_u32_e32 v11, 0, v12
	s_nop 0
	v_addc_co_u32_e32 v53, vcc, 0, v159, vcc
	global_load_dwordx4 v[48:51], v[52:53], off
	v_mul_lo_u32 v3, v14, s26
	v_add_u32_e32 v10, 0, v10
	v_and_b32_e32 v173, 64, v12
	v_bfe_u32 v11, v12, 4, 1
	v_lshl_or_b32 v173, v11, 5, v173
	v_bfe_u32 v11, v12, 5, 1
	v_lshl_or_b32 v173, v11, 3, v173
	v_add_u32_e32 v173, v173, v2
	v_add_co_u32_e64 v2, s[2:3], s23, v8
	v_lshl_add_u64 v[28:29], v[8:9], 0, s[12:13]
	v_add_u32_e32 v172, v10, v3
	v_lshlrev_b64 v[118:119], 9, v[156:157]
	v_add_co_u32_e32 v54, vcc, 0xa1000, v116
	v_addc_co_u32_e64 v3, s[2:3], 0, v9, s[2:3]
	global_load_dwordx4 v[4:7], v[28:29], off offset:64
	v_lshl_add_u64 v[56:57], s[38:39], 0, v[118:119]
	v_addc_co_u32_e32 v55, vcc, 0, v117, vcc
	global_load_dwordx4 v[8:11], v[28:29], off offset:128
	global_load_dwordx4 v[12:15], v[28:29], off offset:192
	global_load_dwordx4 v[16:19], v[28:29], off offset:256
	global_load_dwordx4 v[20:23], v[28:29], off offset:320
	global_load_dwordx4 v[24:27], v[28:29], off offset:384
	s_nop 0
	global_load_dwordx4 v[28:31], v[28:29], off offset:448
	s_nop 0
	global_load_dwordx4 v[32:35], v[2:3], off offset:1024
	s_nop 0
	global_load_dwordx2 v[2:3], v[56:57], off
	v_add_co_u32_e32 v58, vcc, 0xf1000, v116
	s_add_i32 s1, s7, s6
	s_nop 0
	v_addc_co_u32_e32 v59, vcc, 0, v117, vcc
	s_cmp_gt_i32 s1, -1
	s_mov_b64 s[2:3], -1
	s_waitcnt vmcnt(11)
	ds_write_b128 v172, v[40:43]
	ds_write_b64 v173, v[36:37] offset:17408
	ds_write_b64 v173, v[38:39] offset:17424
	s_waitcnt vmcnt(10)
	ds_write_b128 v172, v[44:47] offset:8704
	s_waitcnt vmcnt(9)
	ds_write_b64 v173, v[48:49] offset:26624
	ds_write_b64 v173, v[50:51] offset:26640
	s_waitcnt lgkmcnt(0)
	s_barrier
	global_load_dwordx4 v[44:47], v[58:59], off offset:3072
	global_load_dwordx4 v[36:39], v[54:55], off offset:3072
	global_load_dwordx4 v[48:51], v[52:53], off offset:128
	global_load_dwordx4 v[40:43], v[158:159], off offset:128
	global_load_dwordx2 v[162:163], v[56:57], off offset:8
	v_mad_u32_u24 v52, v60, s26, 0
	v_lshlrev_b32_e32 v53, 7, v60
	v_lshrrev_b32_e32 v54, 2, v120
	v_sub_u32_e32 v53, v52, v53
	v_and_b32_e32 v174, 12, v54
	v_add_u32_e32 v175, v52, v0
	v_lshl_add_u32 v177, v174, 2, v53
	s_cbranch_scc0 .LBB0_1726
	ds_read_b128 v[52:55], v175
	ds_read_b128 v[56:59], v175 offset:64
	ds_read_b128 v[60:63], v175 offset:128
	ds_read_b128 v[64:67], v175 offset:192
	ds_read_b128 v[68:71], v175 offset:4352
	ds_read_b128 v[72:75], v175 offset:4416
	ds_read_b128 v[76:79], v175 offset:4480
	ds_read_b128 v[80:83], v175 offset:4544
	s_mov_b32 s6, s4
	s_mov_b32 s7, s4
	s_mov_b32 s5, s4
	v_mov_b64_e32 v[86:87], s[6:7]
	v_mov_b64_e32 v[84:85], s[4:5]
	s_waitcnt vmcnt(6) lgkmcnt(7)
	s_nop 0
	v_mfma_f32_16x16x32_bf16 v[88:91], v[52:55], v[32:35], v[84:87]
	v_mfma_f32_16x16x32_bf16 v[52:55], v[52:55], v[16:19], v[84:87]
	s_waitcnt lgkmcnt(6)
	v_mfma_f32_16x16x32_bf16 v[88:91], v[56:59], v[4:7], v[88:91]
	v_mfma_f32_16x16x32_bf16 v[52:55], v[56:59], v[20:23], v[52:55]
	s_waitcnt lgkmcnt(5)
	v_mfma_f32_16x16x32_bf16 v[56:59], v[60:63], v[8:11], v[88:91]
	v_mfma_f32_16x16x32_bf16 v[52:55], v[60:63], v[24:27], v[52:55]
	s_waitcnt lgkmcnt(4)
	v_mfma_f32_16x16x32_bf16 v[60:63], v[64:67], v[12:15], v[56:59]
	v_mfma_f32_16x16x32_bf16 v[64:67], v[64:67], v[28:31], v[52:55]
	s_nop 3
	s_nop 0
	ds_read_b128 v[52:55], v175 offset:8704
	ds_read_b128 v[56:59], v175 offset:8768
	ds_read_b128 v[88:91], v175 offset:8832
	ds_read_b128 v[92:95], v175 offset:8896
	s_waitcnt lgkmcnt(7)
	v_mfma_f32_16x16x32_bf16 v[96:99], v[68:71], v[32:35], v[84:87]
	v_mfma_f32_16x16x32_bf16 v[68:71], v[68:71], v[16:19], v[84:87]
	s_waitcnt lgkmcnt(6)
; DEVINL void attn_item(const Params& p, int item, char* smem, int wv) {
;     ...
;     LDK(kfa, 0);
;     LDK(kfb, 1); MMS(kfa, 0);
;     LDK(kfa, 2); MMS(kfb, 1);
;     LDK(kfb, 3); MMS(kfa, 2);
;     LDV(vfa, 0); MMS(kfb, 3);
;     bf16x8 pf[2][2];
;     {
;       const unsigned long long msh = mw >> (fq * 4);
;       const int mlo = (int)(unsigned)msh, mhi = (int)(unsigned)(msh >> 32);
;       int mk[4][4];
; #pragma unroll
;       for (int j = 0; j < 4; ++j) {
;         mk[0][j] = __builtin_amdgcn_sbfe(mlo, j, 1); mk[1][j] = __builtin_amdgcn_sbfe(mlo, 16 + j, 1);
;         mk[2][j] = __builtin_amdgcn_sbfe(mhi, j, 1); mk[3][j] = __builtin_amdgcn_sbfe(mhi, 16 + j, 1);
;       }
; #pragma unroll
;       for (int hh = 0; hh < 2; ++hh) {
;         float mx = s[hh][0][0];
; #pragma unroll
;         for (int kq = 0; kq < 4; ++kq)
; #pragma unroll
;           for (int j = 0; j < 4; ++j) mx = fmaxf(mx, s[hh][kq][j]);
;         {
;           auto r1 = __builtin_amdgcn_permlane16_swap(__float_as_uint(mx), __float_as_uint(mx), false, false);
;           mx = fmaxf(__uint_as_float(r1[0]), __uint_as_float(r1[1]));
;           auto r2 = __builtin_amdgcn_permlane32_swap(__float_as_uint(mx), __float_as_uint(mx), false, false);
;           mx = fmaxf(__uint_as_float(r2[0]), __uint_as_float(r2[1]));
;         }
;         if (kt == 0 || __ballot(mx > 8.f)) {
;           const float delta = (kt == 0) ? mx : fmaxf(mx, 0.f);
;           const float alpha = fexp2(-delta);
;           mrun[hh] += delta;
;           lsum[hh] *= alpha;
; #pragma unroll
;           for (int dt = 0; dt < 8; ++dt) o[hh][dt] *= alpha;
; #pragma unroll
;           for (int kq = 0; kq < 4; ++kq)
; #pragma unroll
;             for (int j = 0; j < 4; ++j) s[hh][kq][j] -= delta;
;         }
;         float ps = 0.f;
;         float pv[4][4];
; #pragma unroll
;         for (int kq = 0; kq < 4; ++kq)
; #pragma unroll
;           for (int j = 0; j < 4; ++j) {
;             pv[kq][j] = __uint_as_float(__float_as_uint(fexp2(s[hh][kq][j])) & (unsigned)mk[kq][j]);
;             ps += pv[kq][j];
;           }
; #pragma unroll
;         for (int c2 = 0; c2 < 2; ++c2) {
;           u32x4 pw;
;           pw[0] = pk2(pv[2 * c2][0], pv[2 * c2][1]); pw[1] = pk2(pv[2 * c2][2], pv[2 * c2][3]);
;           pw[2] = pk2(pv[2 * c2 + 1][0], pv[2 * c2 + 1][1]); pw[3] = pk2(pv[2 * c2 + 1][2], pv[2 * c2 + 1][3]);
	v_mfma_f32_16x16x32_bf16 v[96:99], v[72:75], v[4:7], v[96:99]
	v_mfma_f32_16x16x32_bf16 v[68:71], v[72:75], v[20:23], v[68:71]
	s_waitcnt lgkmcnt(5)
	v_mfma_f32_16x16x32_bf16 v[72:75], v[76:79], v[8:11], v[96:99]
	v_mfma_f32_16x16x32_bf16 v[68:71], v[76:79], v[24:27], v[68:71]
	s_waitcnt lgkmcnt(4)
	v_mfma_f32_16x16x32_bf16 v[72:75], v[80:83], v[12:15], v[72:75]
	v_mfma_f32_16x16x32_bf16 v[68:71], v[80:83], v[28:31], v[68:71]
	ds_read_b128 v[76:79], v175 offset:13056
	ds_read_b128 v[80:83], v175 offset:13120
	ds_read_b128 v[96:99], v175 offset:13184
	ds_read_b128 v[100:103], v175 offset:13248
	s_waitcnt lgkmcnt(7)
	v_mfma_f32_16x16x32_bf16 v[104:107], v[52:55], v[32:35], v[84:87]
	v_mfma_f32_16x16x32_bf16 v[52:55], v[52:55], v[16:19], v[84:87]
	s_waitcnt lgkmcnt(6)
	v_mfma_f32_16x16x32_bf16 v[104:107], v[56:59], v[4:7], v[104:107]
	v_mfma_f32_16x16x32_bf16 v[52:55], v[56:59], v[20:23], v[52:55]
	s_waitcnt lgkmcnt(5)
	v_mfma_f32_16x16x32_bf16 v[56:59], v[88:91], v[8:11], v[104:107]
	v_mfma_f32_16x16x32_bf16 v[52:55], v[88:91], v[24:27], v[52:55]
	s_waitcnt lgkmcnt(4)
	v_mfma_f32_16x16x32_bf16 v[88:91], v[92:95], v[12:15], v[56:59]
	v_mfma_f32_16x16x32_bf16 v[92:95], v[92:95], v[28:31], v[52:55]
	s_nop 2
	s_nop 0
	s_nop 0
	ds_read_b128 v[52:55], v177 offset:17408
	ds_read_b128 v[56:59], v177 offset:17472
	s_waitcnt lgkmcnt(5)
	v_mfma_f32_16x16x32_bf16 v[104:107], v[76:79], v[32:35], v[84:87]
	v_mfma_f32_16x16x32_bf16 v[76:79], v[76:79], v[16:19], v[84:87]
	s_waitcnt lgkmcnt(4)
	v_mfma_f32_16x16x32_bf16 v[84:87], v[80:83], v[4:7], v[104:107]
	v_mfma_f32_16x16x32_bf16 v[76:79], v[80:83], v[20:23], v[76:79]
	s_waitcnt lgkmcnt(3)
	v_mfma_f32_16x16x32_bf16 v[80:83], v[96:99], v[8:11], v[84:87]
	v_mfma_f32_16x16x32_bf16 v[76:79], v[96:99], v[24:27], v[76:79]
	s_waitcnt lgkmcnt(2)
	v_mfma_f32_16x16x32_bf16 v[80:83], v[100:103], v[12:15], v[80:83]
	v_mfma_f32_16x16x32_bf16 v[76:79], v[100:103], v[28:31], v[76:79]
	s_waitcnt vmcnt(5)
	v_lshrrev_b64 v[2:3], v174, v[2:3]
	v_bfe_i32 v0, v2, 0, 1
	v_bfe_i32 v86, v2, 16, 1
	v_bfe_i32 v87, v3, 0, 1
	v_bfe_i32 v96, v3, 16, 1
	v_bfe_i32 v97, v2, 1, 1
	v_bfe_i32 v98, v2, 17, 1
	v_bfe_i32 v99, v3, 1, 1
	v_bfe_i32 v104, v3, 17, 1
	v_bfe_i32 v100, v2, 2, 1
	v_bfe_i32 v101, v2, 18, 1
	v_bfe_i32 v105, v3, 2, 1
	v_bfe_i32 v106, v3, 18, 1
	v_bfe_i32 v102, v2, 3, 1
	v_bfe_i32 v103, v2, 19, 1
	v_bfe_i32 v107, v3, 3, 1
	v_bfe_i32 v108, v3, 19, 1
	v_max_f32_e32 v3, v60, v60
	v_max_f32_e32 v2, v3, v61
	v_max3_f32 v2, v2, v62, v63
	v_max3_f32 v2, v2, v72, v73
	v_max3_f32 v2, v2, v74, v75
	v_max3_f32 v2, v2, v88, v89
	v_max3_f32 v2, v2, v90, v91
	v_max3_f32 v2, v2, v80, v81
	v_max3_f32 v2, v2, v82, v83
	v_mov_b32_e32 v3, v2
	s_nop 1
	v_permlane16_swap_b32_e32 v2, v3
	v_max_f32_e32 v2, v2, v3
	v_mov_b32_e32 v3, v2
	s_nop 1
	v_permlane32_swap_b32_e32 v2, v3
	v_max_f32_e32 v3, v2, v3
	v_sub_f32_e32 v2, v80, v3
	v_sub_f32_e32 v61, v61, v3
	v_sub_f32_e32 v80, v81, v3
	v_sub_f32_e32 v81, v82, v3
	v_sub_f32_e32 v82, v83, v3
	v_sub_f32_e32 v83, v88, v3
	v_sub_f32_e32 v88, v90, v3
	v_exp_f32_e32 v90, v61
	v_exp_f32_e32 v115, v2
	v_max_f32_e32 v61, v64, v64
	v_max_f32_e32 v2, v61, v65
	v_max3_f32 v2, v2, v66, v67
	v_max3_f32 v2, v2, v68, v69
	v_max3_f32 v2, v2, v70, v71
	v_max3_f32 v2, v2, v92, v93
	v_max3_f32 v2, v2, v94, v95
	v_max3_f32 v2, v2, v76, v77
	v_max3_f32 v2, v2, v78, v79
	v_mov_b32_e32 v61, v2
	s_nop 1
	v_permlane16_swap_b32_e32 v2, v61
	v_max_f32_e32 v2, v2, v61
	v_mov_b32_e32 v61, v2
	s_nop 1
	v_permlane32_swap_b32_e32 v2, v61
	v_max_f32_e32 v2, v2, v61
	v_sub_f32_e32 v60, v60, v3
	v_sub_f32_e32 v64, v64, v2
	v_exp_f32_e32 v60, v60
	v_sub_f32_e32 v65, v65, v2
	v_exp_f32_e32 v64, v64
	v_sub_f32_e32 v62, v62, v3
	v_sub_f32_e32 v66, v66, v2
	v_exp_f32_e32 v65, v65
	v_sub_f32_e32 v85, v89, v3
	v_sub_f32_e32 v89, v91, v3
	v_sub_f32_e32 v63, v63, v3
	v_exp_f32_e32 v91, v62
	v_sub_f32_e32 v67, v67, v2
	v_exp_f32_e32 v66, v66
	v_sub_f32_e32 v72, v72, v3
	v_exp_f32_e32 v109, v63
	v_sub_f32_e32 v61, v68, v2
	v_sub_f32_e32 v62, v69, v2
	v_exp_f32_e32 v67, v67
	v_sub_f32_e32 v73, v73, v3
	v_exp_f32_e32 v72, v72
	v_exp_f32_e32 v113, v83
	v_exp_f32_e32 v125, v82
	v_sub_f32_e32 v82, v92, v2
	v_sub_f32_e32 v83, v93, v2
	v_sub_f32_e32 v63, v70, v2
	v_sub_f32_e32 v68, v71, v2
	v_exp_f32_e32 v70, v61
	v_exp_f32_e32 v71, v62
	v_and_b32_e32 v61, v0, v64
	v_and_b32_e32 v60, v0, v60
	v_and_b32_e32 v62, v97, v90
	v_sub_f32_e32 v74, v74, v3
	v_exp_f32_e32 v110, v73
	v_exp_f32_e32 v121, v80
	v_exp_f32_e32 v124, v81
	v_sub_f32_e32 v122, v76, v2
	v_sub_f32_e32 v126, v78, v2
	v_exp_f32_e32 v76, v63
	v_exp_f32_e32 v78, v68
	v_and_b32_e32 v63, v97, v65
	v_cvt_pk_bf16_f32 v68, v60, v62
	v_pk_add_f32 v[80:81], v[60:61], 0 op_sel_hi:[1,0]
	v_exp_f32_e32 v0, v82
	v_exp_f32_e32 v60, v83
	v_sub_f32_e32 v75, v75, v3
	v_exp_f32_e32 v111, v74
	v_and_b32_e32 v65, v100, v66
	v_and_b32_e32 v64, v100, v91
	v_pk_add_f32 v[80:81], v[80:81], v[62:63]
	v_exp_f32_e32 v112, v75
	v_and_b32_e32 v67, v102, v67
	v_and_b32_e32 v66, v102, v109
	v_pk_add_f32 v[80:81], v[80:81], v[64:65]
	v_sub_f32_e32 v93, v95, v2
	v_and_b32_e32 v73, v86, v70
	v_and_b32_e32 v72, v86, v72
	v_pk_add_f32 v[80:81], v[80:81], v[66:67]
	v_exp_f32_e32 v114, v85
	v_sub_f32_e32 v92, v94, v2
	v_and_b32_e32 v75, v98, v71
	v_and_b32_e32 v74, v98, v110
	v_pk_add_f32 v[80:81], v[80:81], v[72:73]
	v_and_b32_e32 v83, v87, v0
	v_and_b32_e32 v82, v87, v113
	v_and_b32_e32 v87, v99, v60
; DEVINL float fexp2(float x) { return __builtin_amdgcn_exp2f(x); }
; DEVINL uint32_t pk2(float a, float b) { hwf2 v = {a, b}; hwbf2 r = __builtin_convertvector(v, hwbf2); return *(uint32_t*)&r; }
; #define MMV(SRC, DT) do { __builtin_amdgcn_s_setprio(1); _Pragma("unroll") for (int c2 = 0; c2 < 2; ++c2) { o[0][DT] = mfma16(SRC[c2], pf[0][c2], o[0][DT]); o[1][DT] = mfma16(SRC[c2], pf[1][c2], o[1][DT]); } __builtin_amdgcn_s_setprio(0); } while (0)
; DEVINL void attn_item(const Params& p, int item, char* smem, int wv) {
;     ...
;         if (kt == 0 || __ballot(mx > 8.f)) {
;           const float delta = (kt == 0) ? mx : fmaxf(mx, 0.f);
;           const float alpha = fexp2(-delta);
;           mrun[hh] += delta;
;           lsum[hh] *= alpha;
; #pragma unroll
;           for (int dt = 0; dt < 8; ++dt) o[hh][dt] *= alpha;
; #pragma unroll
;           for (int kq = 0; kq < 4; ++kq)
; #pragma unroll
;             for (int j = 0; j < 4; ++j) s[hh][kq][j] -= delta;
;         }
;         float ps = 0.f;
;         float pv[4][4];
; #pragma unroll
;         for (int kq = 0; kq < 4; ++kq)
; #pragma unroll
;           for (int j = 0; j < 4; ++j) {
;             pv[kq][j] = __uint_as_float(__float_as_uint(fexp2(s[hh][kq][j])) & (unsigned)mk[kq][j]);
;             ps += pv[kq][j];
;           }
; #pragma unroll
;         for (int c2 = 0; c2 < 2; ++c2) {
;           u32x4 pw;
;           pw[0] = pk2(pv[2 * c2][0], pv[2 * c2][1]); pw[1] = pk2(pv[2 * c2][2], pv[2 * c2][3]);
;           pw[2] = pk2(pv[2 * c2 + 1][0], pv[2 * c2 + 1][1]); pw[3] = pk2(pv[2 * c2 + 1][2], pv[2 * c2 + 1][3]);
;           pf[hh][c2] = *(bf16x8*)&pw;
;         }
;         lsum[hh] += ps;
;       }
;     }
;     LDV(vfb, 1); MMV(vfa, 0);
;     LDV(vfa, 2); MMV(vfb, 1);
;     LDV(vfb, 3); MMV(vfa, 2);
;     LDV(vfa, 4); MMV(vfb, 3);
;     LDV(vfb, 5); MMV(vfa, 4);
;     LDV(vfa, 6); MMV(vfb, 5);
;     LDV(vfb, 7); MMV(vfa, 6);
;     MMV(vfb, 7);
	v_exp_f32_e32 v60, v93
	v_exp_f32_e32 v88, v88
	v_sub_f32_e32 v123, v77, v2
	v_and_b32_e32 v77, v101, v76
	v_and_b32_e32 v76, v101, v111
	v_pk_add_f32 v[80:81], v[80:81], v[74:75]
	v_exp_f32_e32 v0, v92
	v_exp_f32_e32 v89, v89
	v_sub_f32_e32 v127, v79, v2
	v_and_b32_e32 v79, v103, v78
	v_and_b32_e32 v78, v103, v112
	v_pk_add_f32 v[80:81], v[80:81], v[76:77]
	v_exp_f32_e32 v62, v122
	v_pk_add_f32 v[80:81], v[80:81], v[78:79]
	v_cvt_pk_bf16_f32 v69, v64, v66
	v_and_b32_e32 v86, v99, v114
	v_exp_f32_e32 v64, v123
	v_cvt_pk_bf16_f32 v100, v61, v63
	v_cvt_pk_bf16_f32 v102, v73, v75
	v_and_b32_e32 v75, v107, v60
	v_pk_add_f32 v[60:61], v[80:81], v[82:83]
	v_cvt_pk_bf16_f32 v70, v72, v74
	v_exp_f32_e32 v66, v126
	v_and_b32_e32 v73, v105, v0
	v_and_b32_e32 v72, v105, v88
	v_pk_add_f32 v[60:61], v[60:61], v[86:87]
	v_exp_f32_e32 v90, v127
	v_and_b32_e32 v74, v107, v89
	v_pk_add_f32 v[60:61], v[60:61], v[72:73]
	v_cvt_pk_bf16_f32 v71, v76, v78
	v_cvt_pk_bf16_f32 v103, v77, v79
	v_and_b32_e32 v77, v96, v62
	v_and_b32_e32 v76, v96, v115
	v_pk_add_f32 v[60:61], v[60:61], v[74:75]
	v_and_b32_e32 v79, v104, v64
	v_and_b32_e32 v78, v104, v121
	v_pk_add_f32 v[60:61], v[60:61], v[76:77]
	v_and_b32_e32 v89, v106, v66
	v_and_b32_e32 v88, v106, v124
	v_pk_add_f32 v[60:61], v[60:61], v[78:79]
	v_and_b32_e32 v91, v108, v90
	v_and_b32_e32 v90, v108, v125
	v_pk_add_f32 v[60:61], v[60:61], v[88:89]
	v_exp_f32_e64 v84, -v3
	v_exp_f32_e64 v85, -v2
	v_cvt_pk_bf16_f32 v101, v65, v67
	v_pk_add_f32 v[80:81], v[60:61], v[90:91]
	ds_read_b128 v[60:63], v177 offset:19712
	ds_read_b128 v[64:67], v177 offset:19776
	v_pk_add_f32 v[2:3], v[2:3], 0 op_sel_hi:[1,0]
	v_pk_mul_f32 v[122:123], v[84:85], 0 op_sel_hi:[1,0]
	v_pk_fma_f32 v[160:161], v[84:85], 0, v[80:81] op_sel_hi:[1,0,1]
	v_mov_b32_e32 v126, v122
	v_mov_b32_e32 v127, v122
	v_mov_b32_e32 v128, v122
	v_mov_b32_e32 v129, v122
	v_cvt_pk_bf16_f32 v130, v82, v86
	v_cvt_pk_bf16_f32 v131, v72, v74
	v_cvt_pk_bf16_f32 v132, v76, v78
	v_cvt_pk_bf16_f32 v133, v88, v90
	v_mov_b32_e32 v122, v123
	v_mov_b32_e32 v124, v123
	v_mov_b32_e32 v125, v123
	v_cvt_pk_bf16_f32 v134, v83, v87
	v_cvt_pk_bf16_f32 v135, v73, v75
	v_cvt_pk_bf16_f32 v136, v77, v79
	v_cvt_pk_bf16_f32 v137, v89, v91
	s_waitcnt lgkmcnt(3)
	v_mfma_f32_16x16x32_bf16 v[72:75], v[52:55], v[68:71], v[126:129]
	v_mfma_f32_16x16x32_bf16 v[52:55], v[52:55], v[100:103], v[122:125]
	s_waitcnt lgkmcnt(2)
	v_mfma_f32_16x16x32_bf16 v[88:91], v[56:59], v[130:133], v[72:75]
	v_mfma_f32_16x16x32_bf16 v[52:55], v[56:59], v[134:137], v[52:55]
	s_nop 1
	s_nop 0
	s_nop 0
	ds_read_b128 v[72:75], v177 offset:22016
	ds_read_b128 v[76:79], v177 offset:22080
	s_waitcnt lgkmcnt(3)
	v_mfma_f32_16x16x32_bf16 v[56:59], v[60:63], v[68:71], v[126:129]
	v_mfma_f32_16x16x32_bf16 v[60:63], v[60:63], v[100:103], v[122:125]
	s_waitcnt lgkmcnt(2)
	v_mfma_f32_16x16x32_bf16 v[84:87], v[64:67], v[130:133], v[56:59]
	v_mfma_f32_16x16x32_bf16 v[56:59], v[64:67], v[134:137], v[60:63]
	ds_read_b128 v[64:67], v177 offset:24320
	ds_read_b128 v[80:83], v177 offset:24384
	s_waitcnt lgkmcnt(3)
	v_mfma_f32_16x16x32_bf16 v[60:63], v[72:75], v[68:71], v[126:129]
	v_mfma_f32_16x16x32_bf16 v[72:75], v[72:75], v[100:103], v[122:125]
	s_waitcnt lgkmcnt(2)
	v_mfma_f32_16x16x32_bf16 v[92:95], v[76:79], v[130:133], v[60:63]
	v_mfma_f32_16x16x32_bf16 v[60:63], v[76:79], v[134:137], v[72:75]
	s_nop 2
	s_nop 0
	s_nop 0
	ds_read_b128 v[72:75], v177 offset:26624
	ds_read_b128 v[76:79], v177 offset:26688
	s_waitcnt lgkmcnt(3)
	v_mfma_f32_16x16x32_bf16 v[96:99], v[64:67], v[68:71], v[126:129]
	v_mfma_f32_16x16x32_bf16 v[64:67], v[64:67], v[100:103], v[122:125]
	s_waitcnt lgkmcnt(2)
	v_mfma_f32_16x16x32_bf16 v[96:99], v[80:83], v[130:133], v[96:99]
	v_mfma_f32_16x16x32_bf16 v[64:67], v[80:83], v[134:137], v[64:67]
	ds_read_b128 v[80:83], v177 offset:28928
	ds_read_b128 v[112:115], v177 offset:28992
	s_waitcnt lgkmcnt(3)
	v_mfma_f32_16x16x32_bf16 v[104:107], v[72:75], v[68:71], v[126:129]
	v_mfma_f32_16x16x32_bf16 v[72:75], v[72:75], v[100:103], v[122:125]
	s_waitcnt lgkmcnt(2)
	v_mfma_f32_16x16x32_bf16 v[104:107], v[76:79], v[130:133], v[104:107]
	v_mfma_f32_16x16x32_bf16 v[72:75], v[76:79], v[134:137], v[72:75]
	ds_read_b128 v[138:141], v177 offset:31232
	ds_read_b128 v[142:145], v177 offset:31296
	s_waitcnt lgkmcnt(3)
	v_mfma_f32_16x16x32_bf16 v[76:79], v[80:83], v[68:71], v[126:129]
	v_mfma_f32_16x16x32_bf16 v[80:83], v[80:83], v[100:103], v[122:125]
	s_waitcnt lgkmcnt(2)
	v_mfma_f32_16x16x32_bf16 v[108:111], v[112:115], v[130:133], v[76:79]
	v_mfma_f32_16x16x32_bf16 v[76:79], v[112:115], v[134:137], v[80:83]
	ds_read_b128 v[146:149], v177 offset:33536
	ds_read_b128 v[150:153], v177 offset:33600
	s_waitcnt lgkmcnt(3)
	v_mfma_f32_16x16x32_bf16 v[80:83], v[138:141], v[68:71], v[126:129]
	v_mfma_f32_16x16x32_bf16 v[138:141], v[138:141], v[100:103], v[122:125]
	s_waitcnt lgkmcnt(2)
	v_mfma_f32_16x16x32_bf16 v[112:115], v[142:145], v[130:133], v[80:83]
	v_mfma_f32_16x16x32_bf16 v[80:83], v[142:145], v[134:137], v[138:141]
	s_waitcnt lgkmcnt(1)
	v_mfma_f32_16x16x32_bf16 v[68:71], v[146:149], v[68:71], v[126:129]
	v_mfma_f32_16x16x32_bf16 v[122:125], v[146:149], v[100:103], v[122:125]
	s_waitcnt lgkmcnt(0)
	v_mfma_f32_16x16x32_bf16 v[100:103], v[150:153], v[130:133], v[68:71]
	v_mfma_f32_16x16x32_bf16 v[68:71], v[150:153], v[134:137], v[122:125]
	s_cbranch_execz .LBB0_1727
	s_branch .LBB0_1728

; DEVINL float fexp2(float x) { return __builtin_amdgcn_exp2f(x); }
; #define LDK(DST, KQ) _Pragma("unroll") for (int kc = 0; kc < 4; ++kc) DST[kc] = *(const bf16x8*)(Ks + ((KQ) * 16 + fr) * 136 + kc * 32 + fq * 8)
; DEVINL void attn_item(const Params& p, int item, char* smem, int wv) {
;     ...
;     if (kt * 64 <= qlast) {
;     f32x4 s[2][4];
;     bf16x8 kfa[4], kfb[4];
;     bf16x8 vfa[2], vfb[2];
;     ...
;     LDK(kfa, 0);
;     LDK(kfb, 1); MMS(kfa, 0);
;     LDK(kfa, 2); MMS(kfb, 1);
;     LDK(kfb, 3); MMS(kfa, 2);
;     LDV(vfa, 0); MMS(kfb, 3);
;     bf16x8 pf[2][2];
;     {
;       const unsigned long long msh = mw >> (fq * 4);
;       const int mlo = (int)(unsigned)msh, mhi = (int)(unsigned)(msh >> 32);
;       int mk[4][4];
; #pragma unroll
;       for (int j = 0; j < 4; ++j) {
;         mk[0][j] = __builtin_amdgcn_sbfe(mlo, j, 1); mk[1][j] = __builtin_amdgcn_sbfe(mlo, 16 + j, 1);
;         mk[2][j] = __builtin_amdgcn_sbfe(mhi, j, 1); mk[3][j] = __builtin_amdgcn_sbfe(mhi, 16 + j, 1);
;       }
; #pragma unroll
;       for (int hh = 0; hh < 2; ++hh) {
;         float mx = s[hh][0][0];
; #pragma unroll
;         for (int kq = 0; kq < 4; ++kq)
; #pragma unroll
;           for (int j = 0; j < 4; ++j) mx = fmaxf(mx, s[hh][kq][j]);
;         {
;           auto r1 = __builtin_amdgcn_permlane16_swap(__float_as_uint(mx), __float_as_uint(mx), false, false);
;           mx = fmaxf(__uint_as_float(r1[0]), __uint_as_float(r1[1]));
;           auto r2 = __builtin_amdgcn_permlane32_swap(__float_as_uint(mx), __float_as_uint(mx), false, false);
;           mx = fmaxf(__uint_as_float(r2[0]), __uint_as_float(r2[1]));
;         }
;         if (kt == 0 || __ballot(mx > 8.f)) {
;           const float delta = (kt == 0) ? mx : fmaxf(mx, 0.f);
;           const float alpha = fexp2(-delta);
;           mrun[hh] += delta;
;           lsum[hh] *= alpha;
; #pragma unroll
;           for (int dt = 0; dt < 8; ++dt) o[hh][dt] *= alpha;
; #pragma unroll
;           for (int kq = 0; kq < 4; ++kq)
; #pragma unroll
;             for (int j = 0; j < 4; ++j) s[hh][kq][j] -= delta;
.LBB0_1731:
	s_add_i32 s6, s3, 0xffffffa0
	s_cmp_gt_i32 s6, s1
	s_cbranch_scc1 .LBB0_1737
	ds_read_b128 v[116:119], v175
	ds_read_b128 v[120:123], v175 offset:64
	ds_read_b128 v[124:127], v175 offset:128
	ds_read_b128 v[128:131], v175 offset:192
	ds_read_b128 v[132:135], v175 offset:4352
	ds_read_b128 v[140:143], v175 offset:4416
	ds_read_b128 v[144:147], v175 offset:4480
	ds_read_b128 v[178:181], v175 offset:4544
	v_xor_b32_e32 v182, 0x80000000, v3
	v_xor_b32_e32 v186, 0x80000000, v2
	v_mov_b32_e32 v183, v182
	v_mov_b32_e32 v184, v182
	v_mov_b32_e32 v185, v182
	v_mov_b32_e32 v187, v186
	v_mov_b32_e32 v188, v186
	v_mov_b32_e32 v189, v186
	s_waitcnt lgkmcnt(7)
	v_mfma_f32_16x16x32_bf16 v[136:139], v[116:119], v[32:35], v[182:185]
	v_mfma_f32_16x16x32_bf16 v[116:119], v[116:119], v[16:19], v[186:189]
	s_waitcnt lgkmcnt(6)
	v_mfma_f32_16x16x32_bf16 v[136:139], v[120:123], v[4:7], v[136:139]
	v_mfma_f32_16x16x32_bf16 v[116:119], v[120:123], v[20:23], v[116:119]
	s_waitcnt lgkmcnt(5)
	v_mfma_f32_16x16x32_bf16 v[120:123], v[124:127], v[8:11], v[136:139]
	v_mfma_f32_16x16x32_bf16 v[116:119], v[124:127], v[24:27], v[116:119]
	s_waitcnt lgkmcnt(4)
	v_mfma_f32_16x16x32_bf16 v[152:155], v[128:131], v[12:15], v[120:123]
	v_mfma_f32_16x16x32_bf16 v[136:139], v[128:131], v[28:31], v[116:119]
	s_nop 3
	s_nop 0
	ds_read_b128 v[116:119], v175 offset:8704
	ds_read_b128 v[120:123], v175 offset:8768
	ds_read_b128 v[124:127], v175 offset:8832
	ds_read_b128 v[128:131], v175 offset:8896
	s_waitcnt lgkmcnt(7)
	v_mfma_f32_16x16x32_bf16 v[148:151], v[132:135], v[32:35], v[182:185]
	v_mfma_f32_16x16x32_bf16 v[132:135], v[132:135], v[16:19], v[186:189]
	s_waitcnt lgkmcnt(6)
	v_mfma_f32_16x16x32_bf16 v[148:151], v[140:143], v[4:7], v[148:151]
	v_mfma_f32_16x16x32_bf16 v[132:135], v[140:143], v[20:23], v[132:135]
	s_waitcnt lgkmcnt(5)
	v_mfma_f32_16x16x32_bf16 v[140:143], v[144:147], v[8:11], v[148:151]
	v_mfma_f32_16x16x32_bf16 v[132:135], v[144:147], v[24:27], v[132:135]
	s_waitcnt lgkmcnt(4)
	v_mfma_f32_16x16x32_bf16 v[148:151], v[178:181], v[12:15], v[140:143]
	v_mfma_f32_16x16x32_bf16 v[132:135], v[178:181], v[28:31], v[132:135]
	ds_read_b128 v[144:147], v175 offset:13056
	ds_read_b128 v[178:181], v175 offset:13120
	ds_read_b128 v[190:193], v175 offset:13184
	ds_read_b128 v[194:197], v175 offset:13248
	s_waitcnt lgkmcnt(7)
	v_mfma_f32_16x16x32_bf16 v[140:143], v[116:119], v[32:35], v[182:185]
	v_mfma_f32_16x16x32_bf16 v[116:119], v[116:119], v[16:19], v[186:189]
	s_waitcnt lgkmcnt(6)
	v_mfma_f32_16x16x32_bf16 v[140:143], v[120:123], v[4:7], v[140:143]
	v_mfma_f32_16x16x32_bf16 v[116:119], v[120:123], v[20:23], v[116:119]
	s_waitcnt lgkmcnt(5)
	v_mfma_f32_16x16x32_bf16 v[120:123], v[124:127], v[8:11], v[140:143]
	v_mfma_f32_16x16x32_bf16 v[116:119], v[124:127], v[24:27], v[116:119]
	s_waitcnt lgkmcnt(4)
	v_mfma_f32_16x16x32_bf16 v[140:143], v[128:131], v[12:15], v[120:123]
	v_mfma_f32_16x16x32_bf16 v[124:127], v[128:131], v[28:31], v[116:119]
	s_nop 2
	s_nop 0
	s_nop 0
	ds_read_b128 v[116:119], v177 offset:17408
	ds_read_b128 v[120:123], v177 offset:17472
	s_waitcnt lgkmcnt(5)
	v_mfma_f32_16x16x32_bf16 v[128:131], v[144:147], v[32:35], v[182:185]
	v_mfma_f32_16x16x32_bf16 v[144:147], v[144:147], v[16:19], v[186:189]
	s_waitcnt lgkmcnt(4)
	v_mfma_f32_16x16x32_bf16 v[128:131], v[178:181], v[4:7], v[128:131]
	v_mfma_f32_16x16x32_bf16 v[144:147], v[178:181], v[20:23], v[144:147]
	s_waitcnt lgkmcnt(3)
	v_mfma_f32_16x16x32_bf16 v[128:131], v[190:193], v[8:11], v[128:131]
	v_mfma_f32_16x16x32_bf16 v[178:181], v[190:193], v[24:27], v[144:147]
	s_waitcnt lgkmcnt(2)
	v_mfma_f32_16x16x32_bf16 v[144:147], v[194:197], v[12:15], v[128:131]
	v_mfma_f32_16x16x32_bf16 v[128:131], v[194:197], v[28:31], v[178:181]
	s_nop 3
	s_nop 0
	v_max_f32_e32 v179, v152, v152
	v_max_f32_e32 v178, v179, v153
	v_max3_f32 v178, v178, v154, v155
	v_max3_f32 v178, v178, v148, v149
	v_max3_f32 v178, v178, v150, v151
	v_max3_f32 v178, v178, v140, v141
	v_max3_f32 v178, v178, v142, v143
	v_max3_f32 v178, v178, v144, v145
	v_max3_f32 v178, v178, v146, v147
	v_mov_b32_e32 v179, v178
	s_nop 1
	v_permlane16_swap_b32_e32 v178, v179
	v_max_f32_e32 v178, v178, v179
	v_mov_b32_e32 v179, v178
	s_nop 1
	v_permlane32_swap_b32_e32 v178, v179
	v_max_f32_e32 v178, v178, v179
	v_cmp_lt_f32_e32 vcc, s28, v178
	s_cbranch_vccz .LBB0_1734
	v_max_f32_e32 v178, 0, v178
	v_exp_f32_e64 v180, -v178
	v_add_f32_e32 v3, v3, v178
	v_pk_add_f32 v[152:153], v[152:153], v[178:179] op_sel_hi:[1,0] neg_lo:[0,1] neg_hi:[0,1]
	v_pk_add_f32 v[154:155], v[154:155], v[178:179] op_sel_hi:[1,0] neg_lo:[0,1] neg_hi:[0,1]
	v_mul_f32_e32 v160, v160, v180
	v_pk_mul_f32 v[90:91], v[90:91], v[180:181] op_sel_hi:[1,0]
	v_pk_mul_f32 v[88:89], v[88:89], v[180:181] op_sel_hi:[1,0]
	v_pk_mul_f32 v[86:87], v[86:87], v[180:181] op_sel_hi:[1,0]
	v_pk_mul_f32 v[84:85], v[84:85], v[180:181] op_sel_hi:[1,0]
	v_pk_mul_f32 v[94:95], v[94:95], v[180:181] op_sel_hi:[1,0]
	v_pk_mul_f32 v[92:93], v[92:93], v[180:181] op_sel_hi:[1,0]
	v_pk_mul_f32 v[98:99], v[98:99], v[180:181] op_sel_hi:[1,0]
	v_pk_mul_f32 v[96:97], v[96:97], v[180:181] op_sel_hi:[1,0]
	v_pk_mul_f32 v[106:107], v[106:107], v[180:181] op_sel_hi:[1,0]
	v_pk_mul_f32 v[104:105], v[104:105], v[180:181] op_sel_hi:[1,0]
	v_pk_mul_f32 v[110:111], v[110:111], v[180:181] op_sel_hi:[1,0]
	v_pk_mul_f32 v[108:109], v[108:109], v[180:181] op_sel_hi:[1,0]
	v_pk_mul_f32 v[114:115], v[114:115], v[180:181] op_sel_hi:[1,0]
	v_pk_mul_f32 v[112:113], v[112:113], v[180:181] op_sel_hi:[1,0]
	v_pk_mul_f32 v[102:103], v[102:103], v[180:181] op_sel_hi:[1,0]
	v_pk_mul_f32 v[100:101], v[100:101], v[180:181] op_sel_hi:[1,0]
	v_pk_add_f32 v[148:149], v[148:149], v[178:179] op_sel_hi:[1,0] neg_lo:[0,1] neg_hi:[0,1]
	v_pk_add_f32 v[150:151], v[150:151], v[178:179] op_sel_hi:[1,0] neg_lo:[0,1] neg_hi:[0,1]
	v_pk_add_f32 v[140:141], v[140:141], v[178:179] op_sel_hi:[1,0] neg_lo:[0,1] neg_hi:[0,1]
	v_pk_add_f32 v[142:143], v[142:143], v[178:179] op_sel_hi:[1,0] neg_lo:[0,1] neg_hi:[0,1]
	v_pk_add_f32 v[144:145], v[144:145], v[178:179] op_sel_hi:[1,0] neg_lo:[0,1] neg_hi:[0,1]
	v_pk_add_f32 v[146:147], v[146:147], v[178:179] op_sel_hi:[1,0] neg_lo:[0,1] neg_hi:[0,1]
